# grid barrier arrival-counter polling extended to the 12th (last) seam; all seams now release on the arrival counter
# speedup vs baseline: 1.0028x; 1.0028x over previous
; __device__ __forceinline__ unsigned xb_ld(unsigned* p)              { return __hip_atomic_load(p, __ATOMIC_RELAXED, __HIP_MEMORY_SCOPE_AGENT); }
; __device__ __forceinline__ unsigned xb_add(unsigned* p, unsigned v) { return __hip_atomic_fetch_add(p, v, __ATOMIC_RELAXED, __HIP_MEMORY_SCOPE_AGENT); }
; #define XB_SPIN(cond, bar) do { unsigned _sp = 0; while (cond) { __builtin_amdgcn_s_sleep(1); \
;     if ((++_sp & 255u) == 0u) { if (xb_ld(&(bar)[XB_TMO])) break; if (_sp > XB_SPIN_CAP) { atomicAdd(&(bar)[XB_TMO], 1u); break; } } } } while (0)
; __device__ __forceinline__ void xcd_barrier(const XcdBarrier& b) {
;     ...
;         const unsigned old = xb_add(&bar[XB_XSUB(b.x)], 1u);
;         const unsigned gen = old / nloc;
;         if (old + 1u == (gen + 1u) * nloc) {
;             __builtin_amdgcn_fence(__ATOMIC_RELEASE, "agent");
;             asm volatile("s_waitcnt vmcnt(0)" ::: "memory");
;             const unsigned og = xb_add(&bar[XB_TOP], 1u);
;             const unsigned tg = og / nx;
;             if (og + 1u == (tg + 1u) * nx) xb_add(&bar[XB_TOPGEN], 1u);
;             else XB_SPIN(xb_ld(&bar[XB_TOPGEN]) == tg, bar);
;             __builtin_amdgcn_fence(__ATOMIC_ACQUIRE, "agent");
;             xb_add(&bar[XB_XGEN(b.x)], 1u);
;             asm volatile("s_waitcnt vmcnt(0)" ::: "memory");
;         } else {
;             XB_SPIN(xb_ld(&bar[XB_TOPGEN]) == gen, bar);
.LBB0_1337:
	s_or_b64 exec, exec, s[12:13]
	v_cvt_f32_u32_e32 v4, v2
	s_waitcnt vmcnt(0)
	v_readfirstlane_b32 s3, v3
	v_sub_u32_e32 v3, 0, v2
	v_rcp_iflag_f32_e32 v4, v4
	v_add_u32_e32 v5, s3, v1
	v_mul_f32_e32 v4, 0x4f7ffffe, v4
	v_cvt_u32_f32_e32 v4, v4
	v_mul_lo_u32 v1, v3, v4
	v_mul_hi_u32 v1, v4, v1
	v_add_u32_e32 v1, v4, v1
	v_mul_hi_u32 v1, v5, v1
	v_mul_lo_u32 v3, v1, v2
	v_sub_u32_e32 v3, v5, v3
	v_add_u32_e32 v4, 1, v1
	v_cmp_ge_u32_e32 vcc, v3, v2
	s_nop 1
	v_cndmask_b32_e32 v1, v1, v4, vcc
	v_sub_u32_e32 v4, v3, v2
	v_cndmask_b32_e32 v3, v3, v4, vcc
	v_add_u32_e32 v4, 1, v1
	v_cmp_ge_u32_e32 vcc, v3, v2
	v_add_u32_e32 v3, 1, v5
	s_nop 0
	v_cndmask_b32_e32 v1, v1, v4, vcc
	v_mul_lo_u32 v4, v2, v1
	v_add_u32_e32 v2, v4, v2
	v_cmp_ne_u32_e32 vcc, v3, v2
	s_and_saveexec_b64 s[10:11], vcc
	s_xor_b64 s[10:11], exec, s[10:11]
	s_cbranch_execz .LBB0_1351
	s_waitcnt lgkmcnt(0)
	v_mul_lo_u32 v6, v0, v1
	v_add_u32_e32 v6, v6, v0
	v_mov_b32_e32 v0, 0x4000
	global_load_dword v0, v0, s[80:81] offset:1024 sc1
	s_add_u32 s16, s80, 0x4400
	s_addc_u32 s17, s81, 0
	s_waitcnt vmcnt(0)
	v_cmp_lt_u32_e32 vcc, v0, v6
	s_and_saveexec_b64 s[12:13], vcc
	s_cbranch_execz .LBB0_1350
	s_add_u32 s14, s80, 0x1200
	s_addc_u32 s15, s81, 0
	s_mov_b32 s3, 1
	s_mov_b64 s[18:19], 0
	v_mov_b32_e32 v0, 0
	s_branch .LBB0_1341

; __device__ __forceinline__ unsigned xb_ld(unsigned* p)              { return __hip_atomic_load(p, __ATOMIC_RELAXED, __HIP_MEMORY_SCOPE_AGENT); }
; #define XB_SPIN(cond, bar) do { unsigned _sp = 0; while (cond) { __builtin_amdgcn_s_sleep(1); \
;     if ((++_sp & 255u) == 0u) { if (xb_ld(&(bar)[XB_TMO])) break; if (_sp > XB_SPIN_CAP) { atomicAdd(&(bar)[XB_TMO], 1u); break; } } } } while (0)
; __device__ __forceinline__ void xcd_barrier(const XcdBarrier& b) {
;     ...
;         } else {
;             XB_SPIN(xb_ld(&bar[XB_TOPGEN]) == gen, bar);
;             __builtin_amdgcn_fence(__ATOMIC_ACQUIRE, "agent");
.LBB0_1345:
	global_load_dword v2, v0, s[16:17] sc1
	s_add_i32 s3, s3, 1
	s_mov_b64 s[24:25], -1
	s_waitcnt vmcnt(0)
	v_cmp_ge_u32_e32 vcc, v2, v6
	s_orn2_b64 s[22:23], vcc, exec
	s_branch .LBB0_1340

; __device__ __forceinline__ unsigned xb_ld(unsigned* p)              { return __hip_atomic_load(p, __ATOMIC_RELAXED, __HIP_MEMORY_SCOPE_AGENT); }
; __device__ __forceinline__ unsigned xb_add(unsigned* p, unsigned v) { return __hip_atomic_fetch_add(p, v, __ATOMIC_RELAXED, __HIP_MEMORY_SCOPE_AGENT); }
; #define XB_SPIN(cond, bar) do { unsigned _sp = 0; while (cond) { __builtin_amdgcn_s_sleep(1); \
;     if ((++_sp & 255u) == 0u) { if (xb_ld(&(bar)[XB_TMO])) break; if (_sp > XB_SPIN_CAP) { atomicAdd(&(bar)[XB_TMO], 1u); break; } } } } while (0)
; __device__ __forceinline__ void xcd_barrier(const XcdBarrier& b) {
;     ...
;             const unsigned og = xb_add(&bar[XB_TOP], 1u);
;             const unsigned tg = og / nx;
;             if (og + 1u == (tg + 1u) * nx) xb_add(&bar[XB_TOPGEN], 1u);
;             else XB_SPIN(xb_ld(&bar[XB_TOPGEN]) == tg, bar);
.LBB0_1354:
	s_or_b64 exec, exec, s[12:13]
	v_cvt_f32_u32_e32 v3, v0
	s_waitcnt vmcnt(0)
	v_readfirstlane_b32 s3, v2
	s_add_u32 s12, s80, 0x4500
	s_addc_u32 s13, s81, 0
	s_add_u32 s30, s80, 0x4400
	s_addc_u32 s31, s81, 0
	v_rcp_iflag_f32_e32 v3, v3
	v_add_u32_e32 v1, s3, v1
	v_add_u32_e32 v4, 1, v1
	s_mov_b64 s[14:15], -1
	v_mul_f32_e32 v2, 0x4f7ffffe, v3
	v_cvt_u32_f32_e32 v2, v2
	v_sub_u32_e32 v3, 0, v0
	v_mul_lo_u32 v3, v3, v2
	v_mul_hi_u32 v3, v2, v3
	v_add_u32_e32 v2, v2, v3
	v_mul_hi_u32 v2, v1, v2
	v_mul_lo_u32 v3, v2, v0
	v_sub_u32_e32 v1, v1, v3
	v_add_u32_e32 v5, 1, v2
	v_cmp_ge_u32_e32 vcc, v1, v0
	v_sub_u32_e32 v3, v1, v0
	s_nop 0
	v_cndmask_b32_e32 v2, v2, v5, vcc
	v_cndmask_b32_e32 v1, v1, v3, vcc
	v_add_u32_e32 v3, 1, v2
	v_cmp_ge_u32_e32 vcc, v1, v0
	s_nop 1
	v_cndmask_b32_e32 v2, v2, v3, vcc
	v_mul_lo_u32 v1, v0, v2
	v_add_u32_e32 v0, v1, v0
	v_cmp_ne_u32_e32 vcc, v4, v0
	v_mov_b32_e32 v6, v0
	v_mov_b64_e32 v[0:1], s[12:13]
	s_and_saveexec_b64 s[10:11], vcc
	s_cbranch_execz .LBB0_1366
	v_mov_b32_e32 v0, 0
	global_load_dword v1, v0, s[30:31] sc1
	s_mov_b64 s[18:19], 0
	s_waitcnt vmcnt(0)
	v_cmp_lt_u32_e32 vcc, v1, v6
	s_and_saveexec_b64 s[16:17], vcc
	s_cbranch_execz .LBB0_1365
	s_add_u32 s14, s80, 0x1200
	s_addc_u32 s15, s81, 0
	s_mov_b32 s3, 1
	s_branch .LBB0_1358

; __device__ __forceinline__ unsigned xb_ld(unsigned* p)              { return __hip_atomic_load(p, __ATOMIC_RELAXED, __HIP_MEMORY_SCOPE_AGENT); }
; #define XB_SPIN(cond, bar) do { unsigned _sp = 0; while (cond) { __builtin_amdgcn_s_sleep(1); \
;     if ((++_sp & 255u) == 0u) { if (xb_ld(&(bar)[XB_TMO])) break; if (_sp > XB_SPIN_CAP) { atomicAdd(&(bar)[XB_TMO], 1u); break; } } } } while (0)
; __device__ __forceinline__ void xcd_barrier(const XcdBarrier& b) {
;     ...
;             else XB_SPIN(xb_ld(&bar[XB_TOPGEN]) == tg, bar);
.LBB0_1362:
	global_load_dword v1, v0, s[30:31] sc1
	s_add_i32 s3, s3, 1
	s_mov_b64 s[22:23], -1
	s_waitcnt vmcnt(0)
	v_cmp_ge_u32_e32 vcc, v1, v6
	s_orn2_b64 s[26:27], vcc, exec
	s_branch .LBB0_1357
